# adds: GU swiglu epilogue re-emitted with two output dwords interleaved (no wait-state pads), store addresses in free registers
# speedup vs baseline: 1.0154x; 1.0012x over previous
.LBB0_290:
	s_mov_b64 s[22:23], -1
	s_and_b64 vcc, exec, s[0:1]
	v_lshl_add_u32 v149, s11, 8, v1
	v_lshl_or_b32 v144, s10, 7, v147
	v_ashrrev_i32_e32 v145, 31, v144
	v_mov_b64_e32 v[142:143], s[34:35]
	v_lshlrev_b64 v[144:145], 1, v[144:145]
	v_mad_i64_i32 v[214:215], s[10:11], v149, s87, v[142:143]
	v_or_b32_e32 v216, 16, v149
	v_mad_i64_i32 v[216:217], s[10:11], v216, s87, v[142:143]
	v_or_b32_e32 v218, 32, v149
	v_mad_i64_i32 v[218:219], s[10:11], v218, s87, v[142:143]
	v_or_b32_e32 v220, 48, v149
	v_mad_i64_i32 v[220:221], s[10:11], v220, s87, v[142:143]
	v_add_u32_e32 v222, 0x80, v149
	v_mad_i64_i32 v[222:223], s[10:11], v222, s87, v[142:143]
	v_add_u32_e32 v224, 0x90, v149
	v_mad_i64_i32 v[224:225], s[10:11], v224, s87, v[142:143]
	v_add_u32_e32 v226, 0xa0, v149
	v_mad_i64_i32 v[226:227], s[10:11], v226, s87, v[142:143]
	v_add_u32_e32 v236, 0xb0, v149
	v_mad_i64_i32 v[236:237], s[10:11], v236, s87, v[142:143]
	v_lshl_add_u64 v[214:215], v[214:215], 0, v[144:145]
	v_lshl_add_u64 v[216:217], v[216:217], 0, v[144:145]
	v_lshl_add_u64 v[218:219], v[218:219], 0, v[144:145]
	v_lshl_add_u64 v[220:221], v[220:221], 0, v[144:145]
	v_lshl_add_u64 v[222:223], v[222:223], 0, v[144:145]
	v_lshl_add_u64 v[224:225], v[224:225], 0, v[144:145]
	v_lshl_add_u64 v[226:227], v[226:227], 0, v[144:145]
	v_lshl_add_u64 v[236:237], v[236:237], 0, v[144:145]
	v_mul_f32_e32 v150, 0xbfb8aa3b, v122
	v_mul_f32_e32 v152, 0xbfb8aa3b, v124
	v_mul_f32_e32 v151, 0xbfb8aa3b, v123
	v_mul_f32_e32 v153, 0xbfb8aa3b, v125
	v_exp_f32_e32 v150, v150
	v_exp_f32_e32 v152, v152
	v_exp_f32_e32 v151, v151
	v_exp_f32_e32 v153, v153
	v_add_f32_e32 v150, 1.0, v150
	v_add_f32_e32 v152, 1.0, v152
	v_add_f32_e32 v151, 1.0, v151
	v_add_f32_e32 v153, 1.0, v153
	v_rcp_f32_e32 v150, v150
	v_rcp_f32_e32 v152, v152
	v_rcp_f32_e32 v151, v151
	v_rcp_f32_e32 v153, v153
	v_pk_mul_f32 v[122:123], v[122:123], v[150:151]
	v_pk_mul_f32 v[124:125], v[124:125], v[152:153]
	v_pk_mul_f32 v[122:123], v[126:127], v[122:123]
	v_pk_mul_f32 v[124:125], v[128:129], v[124:125]
	v_cvt_pk_bf16_f32 v160, v122, v123
	v_cvt_pk_bf16_f32 v161, v124, v125
	v_mul_f32_e32 v154, 0xbfb8aa3b, v118
	v_mul_f32_e32 v156, 0xbfb8aa3b, v120
	v_mul_f32_e32 v155, 0xbfb8aa3b, v119
	v_mul_f32_e32 v157, 0xbfb8aa3b, v121
	v_exp_f32_e32 v154, v154
	v_exp_f32_e32 v156, v156
	v_exp_f32_e32 v155, v155
	v_exp_f32_e32 v157, v157
	v_add_f32_e32 v154, 1.0, v154
	v_add_f32_e32 v156, 1.0, v156
	v_add_f32_e32 v155, 1.0, v155
	v_add_f32_e32 v157, 1.0, v157
	v_rcp_f32_e32 v154, v154
	v_rcp_f32_e32 v156, v156
	v_rcp_f32_e32 v155, v155
	v_rcp_f32_e32 v157, v157
	v_pk_mul_f32 v[118:119], v[118:119], v[154:155]
	v_pk_mul_f32 v[120:121], v[120:121], v[156:157]
	v_pk_mul_f32 v[118:119], v[114:115], v[118:119]
	v_pk_mul_f32 v[120:121], v[116:117], v[120:121]
	v_cvt_pk_bf16_f32 v162, v118, v119
	v_cvt_pk_bf16_f32 v163, v120, v121
	global_store_dwordx4 v[214:215], v[160:163], off
	v_mul_f32_e32 v150, 0xbfb8aa3b, v110
	v_mul_f32_e32 v152, 0xbfb8aa3b, v112
	v_mul_f32_e32 v151, 0xbfb8aa3b, v111
	v_mul_f32_e32 v153, 0xbfb8aa3b, v113
	v_exp_f32_e32 v150, v150
	v_exp_f32_e32 v152, v152
	v_exp_f32_e32 v151, v151
	v_exp_f32_e32 v153, v153
	v_add_f32_e32 v150, 1.0, v150
	v_add_f32_e32 v152, 1.0, v152
	v_add_f32_e32 v151, 1.0, v151
	v_add_f32_e32 v153, 1.0, v153
	v_rcp_f32_e32 v150, v150
	v_rcp_f32_e32 v152, v152
	v_rcp_f32_e32 v151, v151
	v_rcp_f32_e32 v153, v153
	v_pk_mul_f32 v[110:111], v[110:111], v[150:151]
	v_pk_mul_f32 v[112:113], v[112:113], v[152:153]
	v_pk_mul_f32 v[110:111], v[106:107], v[110:111]
	v_pk_mul_f32 v[112:113], v[108:109], v[112:113]
	v_cvt_pk_bf16_f32 v164, v110, v111
	v_cvt_pk_bf16_f32 v165, v112, v113
	v_mul_f32_e32 v154, 0xbfb8aa3b, v102
	v_mul_f32_e32 v156, 0xbfb8aa3b, v104
	v_mul_f32_e32 v155, 0xbfb8aa3b, v103
	v_mul_f32_e32 v157, 0xbfb8aa3b, v105
	v_exp_f32_e32 v154, v154
	v_exp_f32_e32 v156, v156
	v_exp_f32_e32 v155, v155
	v_exp_f32_e32 v157, v157
	v_add_f32_e32 v154, 1.0, v154
	v_add_f32_e32 v156, 1.0, v156
	v_add_f32_e32 v155, 1.0, v155
	v_add_f32_e32 v157, 1.0, v157
	v_rcp_f32_e32 v154, v154
	v_rcp_f32_e32 v156, v156
	v_rcp_f32_e32 v155, v155
	v_rcp_f32_e32 v157, v157
	v_pk_mul_f32 v[102:103], v[102:103], v[154:155]
	v_pk_mul_f32 v[104:105], v[104:105], v[156:157]
	v_pk_mul_f32 v[102:103], v[98:99], v[102:103]
	v_pk_mul_f32 v[104:105], v[100:101], v[104:105]
	v_cvt_pk_bf16_f32 v166, v102, v103
	v_cvt_pk_bf16_f32 v167, v104, v105
	global_store_dwordx4 v[216:217], v[164:167], off
	v_mul_f32_e32 v150, 0xbfb8aa3b, v94
	v_mul_f32_e32 v152, 0xbfb8aa3b, v96
	v_mul_f32_e32 v151, 0xbfb8aa3b, v95
	v_mul_f32_e32 v153, 0xbfb8aa3b, v97
	v_exp_f32_e32 v150, v150
	v_exp_f32_e32 v152, v152
	v_exp_f32_e32 v151, v151
	v_exp_f32_e32 v153, v153
	v_add_f32_e32 v150, 1.0, v150
	v_add_f32_e32 v152, 1.0, v152
	v_add_f32_e32 v151, 1.0, v151
	v_add_f32_e32 v153, 1.0, v153
	v_rcp_f32_e32 v150, v150
	v_rcp_f32_e32 v152, v152
	v_rcp_f32_e32 v151, v151
	v_rcp_f32_e32 v153, v153
	v_pk_mul_f32 v[94:95], v[94:95], v[150:151]
	v_pk_mul_f32 v[96:97], v[96:97], v[152:153]
	v_pk_mul_f32 v[94:95], v[90:91], v[94:95]
	v_pk_mul_f32 v[96:97], v[92:93], v[96:97]
	v_cvt_pk_bf16_f32 v168, v94, v95
	v_cvt_pk_bf16_f32 v169, v96, v97
	v_mul_f32_e32 v154, 0xbfb8aa3b, v86
	v_mul_f32_e32 v156, 0xbfb8aa3b, v88
	v_mul_f32_e32 v155, 0xbfb8aa3b, v87
	v_mul_f32_e32 v157, 0xbfb8aa3b, v89
	v_exp_f32_e32 v154, v154
	v_exp_f32_e32 v156, v156
	v_exp_f32_e32 v155, v155
	v_exp_f32_e32 v157, v157
	v_add_f32_e32 v154, 1.0, v154
	v_add_f32_e32 v156, 1.0, v156
	v_add_f32_e32 v155, 1.0, v155
	v_add_f32_e32 v157, 1.0, v157
	v_rcp_f32_e32 v154, v154
	v_rcp_f32_e32 v156, v156
	v_rcp_f32_e32 v155, v155
	v_rcp_f32_e32 v157, v157
	v_pk_mul_f32 v[86:87], v[86:87], v[154:155]
	v_pk_mul_f32 v[88:89], v[88:89], v[156:157]
	v_pk_mul_f32 v[86:87], v[82:83], v[86:87]
	v_pk_mul_f32 v[88:89], v[84:85], v[88:89]
	v_cvt_pk_bf16_f32 v170, v86, v87
	v_cvt_pk_bf16_f32 v171, v88, v89
	global_store_dwordx4 v[218:219], v[168:171], off
	v_mul_f32_e32 v150, 0xbfb8aa3b, v78
	v_mul_f32_e32 v152, 0xbfb8aa3b, v80
	v_mul_f32_e32 v151, 0xbfb8aa3b, v79
	v_mul_f32_e32 v153, 0xbfb8aa3b, v81
	v_exp_f32_e32 v150, v150
	v_exp_f32_e32 v152, v152
	v_exp_f32_e32 v151, v151
	v_exp_f32_e32 v153, v153
	v_add_f32_e32 v150, 1.0, v150
	v_add_f32_e32 v152, 1.0, v152
	v_add_f32_e32 v151, 1.0, v151
	v_add_f32_e32 v153, 1.0, v153
	v_rcp_f32_e32 v150, v150
	v_rcp_f32_e32 v152, v152
	v_rcp_f32_e32 v151, v151
	v_rcp_f32_e32 v153, v153
	v_pk_mul_f32 v[78:79], v[78:79], v[150:151]
	v_pk_mul_f32 v[80:81], v[80:81], v[152:153]
	v_pk_mul_f32 v[78:79], v[74:75], v[78:79]
	v_pk_mul_f32 v[80:81], v[76:77], v[80:81]
	v_cvt_pk_bf16_f32 v172, v78, v79
	v_cvt_pk_bf16_f32 v173, v80, v81
	v_mul_f32_e32 v154, 0xbfb8aa3b, v70
	v_mul_f32_e32 v156, 0xbfb8aa3b, v72
	v_mul_f32_e32 v155, 0xbfb8aa3b, v71
	v_mul_f32_e32 v157, 0xbfb8aa3b, v73
	v_exp_f32_e32 v154, v154
	v_exp_f32_e32 v156, v156
	v_exp_f32_e32 v155, v155
	v_exp_f32_e32 v157, v157
	v_add_f32_e32 v154, 1.0, v154
	v_add_f32_e32 v156, 1.0, v156
	v_add_f32_e32 v155, 1.0, v155
	v_add_f32_e32 v157, 1.0, v157
	v_rcp_f32_e32 v154, v154
	v_rcp_f32_e32 v156, v156
	v_rcp_f32_e32 v155, v155
	v_rcp_f32_e32 v157, v157
	v_pk_mul_f32 v[70:71], v[70:71], v[154:155]
	v_pk_mul_f32 v[72:73], v[72:73], v[156:157]
	v_pk_mul_f32 v[70:71], v[66:67], v[70:71]
	v_pk_mul_f32 v[72:73], v[68:69], v[72:73]
	v_cvt_pk_bf16_f32 v174, v70, v71
	v_cvt_pk_bf16_f32 v175, v72, v73
	global_store_dwordx4 v[220:221], v[172:175], off
	v_mul_f32_e32 v150, 0xbfb8aa3b, v62
	v_mul_f32_e32 v152, 0xbfb8aa3b, v64
	v_mul_f32_e32 v151, 0xbfb8aa3b, v63
	v_mul_f32_e32 v153, 0xbfb8aa3b, v65
	v_exp_f32_e32 v150, v150
	v_exp_f32_e32 v152, v152
	v_exp_f32_e32 v151, v151
	v_exp_f32_e32 v153, v153
	v_add_f32_e32 v150, 1.0, v150
	v_add_f32_e32 v152, 1.0, v152
	v_add_f32_e32 v151, 1.0, v151
	v_add_f32_e32 v153, 1.0, v153
	v_rcp_f32_e32 v150, v150
	v_rcp_f32_e32 v152, v152
	v_rcp_f32_e32 v151, v151
	v_rcp_f32_e32 v153, v153
	v_pk_mul_f32 v[62:63], v[62:63], v[150:151]
	v_pk_mul_f32 v[64:65], v[64:65], v[152:153]
	v_pk_mul_f32 v[62:63], v[58:59], v[62:63]
	v_pk_mul_f32 v[64:65], v[60:61], v[64:65]
	v_cvt_pk_bf16_f32 v176, v62, v63
	v_cvt_pk_bf16_f32 v177, v64, v65
	v_mul_f32_e32 v154, 0xbfb8aa3b, v54
	v_mul_f32_e32 v156, 0xbfb8aa3b, v56
	v_mul_f32_e32 v155, 0xbfb8aa3b, v55
	v_mul_f32_e32 v157, 0xbfb8aa3b, v57
	v_exp_f32_e32 v154, v154
	v_exp_f32_e32 v156, v156
	v_exp_f32_e32 v155, v155
	v_exp_f32_e32 v157, v157
	v_add_f32_e32 v154, 1.0, v154
	v_add_f32_e32 v156, 1.0, v156
	v_add_f32_e32 v155, 1.0, v155
	v_add_f32_e32 v157, 1.0, v157
	v_rcp_f32_e32 v154, v154
	v_rcp_f32_e32 v156, v156
	v_rcp_f32_e32 v155, v155
	v_rcp_f32_e32 v157, v157
	v_pk_mul_f32 v[54:55], v[54:55], v[154:155]
	v_pk_mul_f32 v[56:57], v[56:57], v[156:157]
	v_pk_mul_f32 v[54:55], v[50:51], v[54:55]
	v_pk_mul_f32 v[56:57], v[52:53], v[56:57]
	v_cvt_pk_bf16_f32 v178, v54, v55
	v_cvt_pk_bf16_f32 v179, v56, v57
	global_store_dwordx4 v[222:223], v[176:179], off
	v_mul_f32_e32 v150, 0xbfb8aa3b, v46
	v_mul_f32_e32 v152, 0xbfb8aa3b, v48
	v_mul_f32_e32 v151, 0xbfb8aa3b, v47
	v_mul_f32_e32 v153, 0xbfb8aa3b, v49
	v_exp_f32_e32 v150, v150
	v_exp_f32_e32 v152, v152
	v_exp_f32_e32 v151, v151
	v_exp_f32_e32 v153, v153
	v_add_f32_e32 v150, 1.0, v150
	v_add_f32_e32 v152, 1.0, v152
	v_add_f32_e32 v151, 1.0, v151
	v_add_f32_e32 v153, 1.0, v153
	v_rcp_f32_e32 v150, v150
	v_rcp_f32_e32 v152, v152
	v_rcp_f32_e32 v151, v151
	v_rcp_f32_e32 v153, v153
	v_pk_mul_f32 v[46:47], v[46:47], v[150:151]
	v_pk_mul_f32 v[48:49], v[48:49], v[152:153]
	v_pk_mul_f32 v[46:47], v[42:43], v[46:47]
	v_pk_mul_f32 v[48:49], v[44:45], v[48:49]
	v_cvt_pk_bf16_f32 v180, v46, v47
	v_cvt_pk_bf16_f32 v181, v48, v49
	v_mul_f32_e32 v154, 0xbfb8aa3b, v38
	v_mul_f32_e32 v156, 0xbfb8aa3b, v40
	v_mul_f32_e32 v155, 0xbfb8aa3b, v39
	v_mul_f32_e32 v157, 0xbfb8aa3b, v41
	v_exp_f32_e32 v154, v154
	v_exp_f32_e32 v156, v156
	v_exp_f32_e32 v155, v155
	v_exp_f32_e32 v157, v157
	v_add_f32_e32 v154, 1.0, v154
	v_add_f32_e32 v156, 1.0, v156
	v_add_f32_e32 v155, 1.0, v155
	v_add_f32_e32 v157, 1.0, v157
	v_rcp_f32_e32 v154, v154
	v_rcp_f32_e32 v156, v156
	v_rcp_f32_e32 v155, v155
	v_rcp_f32_e32 v157, v157
	v_pk_mul_f32 v[38:39], v[38:39], v[154:155]
	v_pk_mul_f32 v[40:41], v[40:41], v[156:157]
	v_pk_mul_f32 v[38:39], v[34:35], v[38:39]
	v_pk_mul_f32 v[40:41], v[36:37], v[40:41]
	v_cvt_pk_bf16_f32 v182, v38, v39
	v_cvt_pk_bf16_f32 v183, v40, v41
	global_store_dwordx4 v[224:225], v[180:183], off
	v_mul_f32_e32 v150, 0xbfb8aa3b, v30
	v_mul_f32_e32 v152, 0xbfb8aa3b, v32
	v_mul_f32_e32 v151, 0xbfb8aa3b, v31
	v_mul_f32_e32 v153, 0xbfb8aa3b, v33
	v_exp_f32_e32 v150, v150
	v_exp_f32_e32 v152, v152
	v_exp_f32_e32 v151, v151
	v_exp_f32_e32 v153, v153
	v_add_f32_e32 v150, 1.0, v150
	v_add_f32_e32 v152, 1.0, v152
	v_add_f32_e32 v151, 1.0, v151
	v_add_f32_e32 v153, 1.0, v153
	v_rcp_f32_e32 v150, v150
	v_rcp_f32_e32 v152, v152
	v_rcp_f32_e32 v151, v151
	v_rcp_f32_e32 v153, v153
	v_pk_mul_f32 v[30:31], v[30:31], v[150:151]
	v_pk_mul_f32 v[32:33], v[32:33], v[152:153]
	v_pk_mul_f32 v[30:31], v[26:27], v[30:31]
	v_pk_mul_f32 v[32:33], v[28:29], v[32:33]
	v_cvt_pk_bf16_f32 v184, v30, v31
	v_cvt_pk_bf16_f32 v185, v32, v33
	v_mul_f32_e32 v154, 0xbfb8aa3b, v22
	v_mul_f32_e32 v156, 0xbfb8aa3b, v24
	v_mul_f32_e32 v155, 0xbfb8aa3b, v23
	v_mul_f32_e32 v157, 0xbfb8aa3b, v25
	v_exp_f32_e32 v154, v154
	v_exp_f32_e32 v156, v156
	v_exp_f32_e32 v155, v155
	v_exp_f32_e32 v157, v157
	v_add_f32_e32 v154, 1.0, v154
	v_add_f32_e32 v156, 1.0, v156
	v_add_f32_e32 v155, 1.0, v155
	v_add_f32_e32 v157, 1.0, v157
	v_rcp_f32_e32 v154, v154
	v_rcp_f32_e32 v156, v156
	v_rcp_f32_e32 v155, v155
	v_rcp_f32_e32 v157, v157
	v_pk_mul_f32 v[22:23], v[22:23], v[154:155]
	v_pk_mul_f32 v[24:25], v[24:25], v[156:157]
	v_pk_mul_f32 v[22:23], v[18:19], v[22:23]
	v_pk_mul_f32 v[24:25], v[20:21], v[24:25]
	v_cvt_pk_bf16_f32 v186, v22, v23
	v_cvt_pk_bf16_f32 v187, v24, v25
	global_store_dwordx4 v[226:227], v[184:187], off
	v_mul_f32_e32 v150, 0xbfb8aa3b, v14
	v_mul_f32_e32 v152, 0xbfb8aa3b, v16
	v_mul_f32_e32 v151, 0xbfb8aa3b, v15
	v_mul_f32_e32 v153, 0xbfb8aa3b, v17
	v_exp_f32_e32 v150, v150
	v_exp_f32_e32 v152, v152
	v_exp_f32_e32 v151, v151
	v_exp_f32_e32 v153, v153
	v_add_f32_e32 v150, 1.0, v150
	v_add_f32_e32 v152, 1.0, v152
	v_add_f32_e32 v151, 1.0, v151
	v_add_f32_e32 v153, 1.0, v153
	v_rcp_f32_e32 v150, v150
	v_rcp_f32_e32 v152, v152
	v_rcp_f32_e32 v151, v151
	v_rcp_f32_e32 v153, v153
	v_pk_mul_f32 v[14:15], v[14:15], v[150:151]
	v_pk_mul_f32 v[16:17], v[16:17], v[152:153]
	v_pk_mul_f32 v[14:15], v[10:11], v[14:15]
	v_pk_mul_f32 v[16:17], v[12:13], v[16:17]
	v_cvt_pk_bf16_f32 v188, v14, v15
	v_cvt_pk_bf16_f32 v189, v16, v17
	v_mul_f32_e32 v154, 0xbfb8aa3b, v6
	v_mul_f32_e32 v156, 0xbfb8aa3b, v8
	v_mul_f32_e32 v155, 0xbfb8aa3b, v7
	v_mul_f32_e32 v157, 0xbfb8aa3b, v9
	v_exp_f32_e32 v154, v154
	v_exp_f32_e32 v156, v156
	v_exp_f32_e32 v155, v155
	v_exp_f32_e32 v157, v157
	v_add_f32_e32 v154, 1.0, v154
	v_add_f32_e32 v156, 1.0, v156
	v_add_f32_e32 v155, 1.0, v155
	v_add_f32_e32 v157, 1.0, v157
	v_rcp_f32_e32 v154, v154
	v_rcp_f32_e32 v156, v156
	v_rcp_f32_e32 v155, v155
	v_rcp_f32_e32 v157, v157
	v_pk_mul_f32 v[6:7], v[6:7], v[154:155]
	v_pk_mul_f32 v[8:9], v[8:9], v[156:157]
	v_pk_mul_f32 v[6:7], v[2:3], v[6:7]
	v_pk_mul_f32 v[8:9], v[4:5], v[8:9]
	v_cvt_pk_bf16_f32 v190, v6, v7
	v_cvt_pk_bf16_f32 v191, v8, v9
	global_store_dwordx4 v[236:237], v[188:191], off
	s_cbranch_vccnz .LBB0_278
	s_andn2_b64 vcc, exec, s[14:15]
	s_cbranch_vccnz .LBB0_277
	s_barrier
	s_branch .LBB0_277
